# chunk_output P5/P18: norm weights loaded once, next-chunk prefetch kept in flight across norm (no vmcnt(0) drain), gate words via v224-231
# baseline (speedup 1.0000x reference)
.LBB0_620:
	s_add_u32 s0, s94, 0x62d00000
	v_writelane_b32 v246, s0, 11
	s_addc_u32 s0, s95, 0
	s_cmp_lt_i32 s64, 6
	s_cselect_b64 s[2:3], -1, 0
	s_cmp_gt_i32 s64, 5
	v_writelane_b32 v246, s0, 19
	s_cselect_b64 s[0:1], -1, 0
	s_cmp_lt_i32 s65, 6
	s_cselect_b64 s[4:5], -1, 0
	s_or_b64 s[0:1], s[0:1], s[4:5]
	s_and_b64 vcc, exec, s[0:1]
	s_cbranch_vccnz .LBB0_628
	s_cmpk_gt_i32 s88, 0x7ff
	s_cbranch_scc1 .LBB0_628
	s_add_u32 s0, s94, 0x42503000
	s_addc_u32 s1, s95, 0
	v_readlane_b32 s21, v247, 0
	s_ashr_i32 s10, s88, 9
	s_lshl_b32 s14, s88, 6
	s_ashr_i32 s89, s88, 31
	s_lshr_b32 s4, s21, 7
	s_bfe_u32 s20, s21, 0x10006
	s_ashr_i32 s11, s10, 31
	s_and_b32 s15, s14, 0x7c0
	s_lshl_b64 s[12:13], s[88:89], 14
	s_add_u32 s6, s70, s12
	s_waitcnt vmcnt(0)
	v_and_b32_e32 v1, 31, v0
	s_addc_u32 s7, s71, s13
	s_lshl_b32 s22, s20, 13
	v_lshl_or_b32 v2, v1, 8, s22
	v_mov_b32_e32 v3, 0
	v_lshl_add_u64 v[4:5], s[6:7], 0, v[2:3]
	s_lshl_b64 s[6:7], s[88:89], 15
	v_readlane_b32 s25, v246, 11
	s_mov_b32 s5, 0
	s_add_u32 s8, s25, s6
	v_readlane_b32 s26, v246, 19
	v_lshrrev_b32_e32 v112, 5, v162
	s_addc_u32 s9, s26, s7
	s_lshl_b64 s[6:7], s[4:5], 13
	v_lshlrev_b32_e32 v6, 4, v112
	v_mov_b32_e32 v7, v3
	s_add_u32 s8, s8, s6
	v_lshl_add_u64 v[4:5], v[4:5], 0, v[6:7]
	s_addc_u32 s9, s9, s7
	v_lshlrev_b32_e32 v8, 4, v162
	v_mov_b32_e32 v9, v3
	s_lshl_b64 s[10:11], s[10:11], 11
	v_readlane_b32 s23, v247, 37
	v_lshl_add_u64 v[10:11], s[8:9], 0, v[8:9]
	global_load_dwordx4 v[18:21], v[4:5], off
	global_load_dwordx4 v[22:25], v[4:5], off offset:32
	global_load_dwordx4 v[26:29], v8, s[8:9]
	global_load_dwordx4 v[30:33], v8, s[8:9] offset:1024
	global_load_dwordx4 v[34:37], v[4:5], off offset:64
	global_load_dwordx4 v[38:41], v[4:5], off offset:96
	global_load_dwordx4 v[42:45], v8, s[8:9] offset:2048
	global_load_dwordx4 v[46:49], v8, s[8:9] offset:3072
	s_add_u32 s8, s23, s12
	v_readlane_b32 s24, v247, 38
	s_addc_u32 s12, s24, s13
	s_add_u32 s8, s8, s22
	s_movk_i32 s9, 0x1000
	s_addc_u32 s13, s12, 0
	s_lshl_b32 s4, s4, 6
	v_add_co_u32_e32 v10, vcc, s9, v10
	s_add_u32 s12, s8, s4
	s_nop 0
	v_addc_co_u32_e32 v11, vcc, 0, v11, vcc
	global_load_dwordx4 v[50:53], v[4:5], off offset:128
	global_load_dwordx4 v[54:57], v[4:5], off offset:160
	global_load_dwordx4 v[58:61], v[10:11], off
	global_load_dwordx4 v[62:65], v[10:11], off offset:1024
	global_load_dwordx4 v[66:69], v[4:5], off offset:192
	global_load_dwordx4 v[70:73], v[4:5], off offset:224
	global_load_dwordx4 v[74:77], v[10:11], off offset:2048
	global_load_dwordx4 v[78:81], v[10:11], off offset:3072
	s_addc_u32 s13, s13, 0
	v_lshlrev_b32_e32 v4, 1, v1
	v_mov_b32_e32 v5, v3
	v_lshl_add_u64 v[10:11], s[12:13], 0, v[4:5]
	v_readlane_b32 s13, v247, 9
	v_lshlrev_b32_e32 v12, 10, v112
	v_mov_b32_e32 v13, v3
	s_or_b32 s8, s10, s15
	s_lshl_b32 s16, s13, 3
	v_lshl_add_u64 v[10:11], v[10:11], 0, v[12:13]
	s_add_u32 s8, s8, s16
	v_readlane_b32 s10, v247, 10
	global_load_ushort v95, v[10:11], off
	global_load_ushort v96, v[10:11], off offset:256
	global_load_ushort v97, v[10:11], off offset:512
	global_load_ushort v98, v[10:11], off offset:768
	global_load_ushort v99, v[10:11], off offset:2048
	global_load_ushort v100, v[10:11], off offset:2304
	global_load_ushort v101, v[10:11], off offset:2560
	global_load_ushort v102, v[10:11], off offset:2816
	v_add_co_u32_e32 v10, vcc, s9, v10
	s_addc_u32 s12, s11, 0
	s_lshl_b32 s15, s88, 2
	s_and_b32 s10, s10, 0xf00
	v_addc_co_u32_e32 v11, vcc, 0, v11, vcc
	s_add_u32 s10, s0, s10
	global_load_ushort v103, v[10:11], off
	global_load_ushort v104, v[10:11], off offset:256
	global_load_ushort v105, v[10:11], off offset:512
	global_load_ushort v106, v[10:11], off offset:768
	global_load_ushort v107, v[10:11], off offset:2048
	global_load_ushort v108, v[10:11], off offset:2304
	global_load_ushort v109, v[10:11], off offset:2560
	global_load_ushort v110, v[10:11], off offset:2816
	s_addc_u32 s11, s1, 0
	v_lshlrev_b32_e32 v10, 2, v162
	v_mov_b32_e32 v11, v3
	v_lshl_add_u64 v[14:15], s[10:11], 0, v[10:11]
	v_mov_b32_e32 v94, 0x6800
	s_mulk_i32 s12, 0x6800
	v_mad_u64_u32 v[14:15], s[10:11], s8, v94, v[14:15]
	s_movk_i32 s17, 0x6000
	v_add_u32_e32 v15, s12, v15
	v_add_co_u32_e32 v16, vcc, s17, v14
	s_mov_b32 s18, 0xd000
	s_nop 0
	v_addc_co_u32_e32 v17, vcc, 0, v15, vcc
	v_add_co_u32_e32 v82, vcc, s18, v14
	s_mov_b32 s19, 0x13000
	s_nop 0
	v_addc_co_u32_e32 v83, vcc, 0, v15, vcc
	v_add_co_u32_e32 v84, vcc, s19, v14
	s_mov_b32 s8, 0x1a000
	s_nop 0
	v_addc_co_u32_e32 v85, vcc, 0, v15, vcc
	v_add_co_u32_e32 v86, vcc, s8, v14
	s_mov_b32 s8, 0x20000
	s_nop 0
	v_addc_co_u32_e32 v87, vcc, 0, v15, vcc
	v_add_co_u32_e32 v88, vcc, s8, v14
	s_mov_b32 s8, 0x27000
	s_nop 0
	v_addc_co_u32_e32 v89, vcc, 0, v15, vcc
	v_add_co_u32_e32 v90, vcc, s8, v14
	s_mov_b32 s8, 0x2d000
	s_nop 0
	v_addc_co_u32_e32 v91, vcc, 0, v15, vcc
	v_add_co_u32_e32 v92, vcc, s8, v14
	s_lshl_b32 s20, s20, 14
	s_nop 0
	v_addc_co_u32_e32 v93, vcc, 0, v15, vcc
	global_load_dword v224, v[14:15], off
	global_load_dword v225, v[16:17], off offset:2048
	global_load_dword v226, v[82:83], off
	global_load_dword v227, v[84:85], off offset:2048
	global_load_dword v228, v[86:87], off
	global_load_dword v229, v[88:89], off offset:2048
	global_load_dword v230, v[90:91], off
	global_load_dword v231, v[92:93], off offset:2048
	s_and_b32 s21, s21, 0xffffff80
	s_add_u32 s6, s25, s6
	s_addc_u32 s7, s26, s7
	v_lshl_add_u64 v[84:85], s[6:7], 0, v[8:9]
	s_add_u32 s6, s23, s22
	s_addc_u32 s7, s24, 0
	s_add_u32 s6, s6, s4
	v_mov_b32_e32 v15, v3
	v_lshl_add_u64 v[2:3], s[70:71], 0, v[2:3]
	s_addc_u32 s7, s7, 0
	v_lshl_add_u64 v[82:83], v[2:3], 0, v[6:7]
	v_lshl_add_u64 v[2:3], s[6:7], 0, v[4:5]
	v_mbcnt_hi_u32_b32 v4, -1, v163
	v_and_b32_e32 v5, 64, v4
	v_add_u32_e32 v5, 64, v5
	v_xor_b32_e32 v6, 1, v4
	v_cmp_lt_i32_e32 vcc, v6, v5
	v_readlane_b32 s10, v247, 3
	v_readlane_b32 s11, v247, 4
	v_cndmask_b32_e32 v6, v4, v6, vcc
	v_lshlrev_b32_e32 v113, 2, v6
	v_xor_b32_e32 v6, 2, v4
	v_cmp_lt_i32_e32 vcc, v6, v5
	s_load_dwordx2 s[10:11], s[10:11], 0x40
	v_lshl_add_u64 v[86:87], s[0:1], 0, v[10:11]
	v_cndmask_b32_e32 v6, v4, v6, vcc
	v_lshlrev_b32_e32 v114, 2, v6
	v_xor_b32_e32 v6, 4, v4
	v_cmp_lt_i32_e32 vcc, v6, v5
	v_readlane_b32 s0, v247, 47
	v_lshlrev_b32_e32 v14, 3, v162
	v_cndmask_b32_e32 v6, v4, v6, vcc
	v_lshlrev_b32_e32 v115, 2, v6
	v_xor_b32_e32 v6, 8, v4
	v_cmp_lt_i32_e32 vcc, v6, v5
	v_readlane_b32 s1, v247, 48
	s_or_b32 s22, s16, 1
	v_cndmask_b32_e32 v6, v4, v6, vcc
	v_lshlrev_b32_e32 v116, 2, v6
	v_xor_b32_e32 v6, 16, v4
	v_cmp_lt_i32_e32 vcc, v6, v5
	s_or_b32 s24, s16, 2
	s_or_b32 s26, s16, 3
	v_cndmask_b32_e32 v6, v4, v6, vcc
	v_lshlrev_b32_e32 v117, 2, v6
	v_xor_b32_e32 v6, 32, v4
	v_cmp_lt_i32_e32 vcc, v6, v5
	s_or_b32 s28, s16, 4
	s_or_b32 s30, s16, 5
	v_cndmask_b32_e32 v4, v4, v6, vcc
	s_or_b32 s33, s16, 6
	s_or_b32 s35, s16, 7
	v_lshlrev_b32_e32 v111, 1, v162
	v_lshlrev_b32_e32 v112, 11, v112
	v_lshlrev_b32_e32 v118, 2, v4
	s_waitcnt lgkmcnt(0)
	v_lshl_add_u64 v[88:89], s[10:11], 0, v[14:15]
	global_load_dwordx2 v[222:223], v[88:89], off
	global_load_dword v232, v[88:89], off
	global_load_dword v232, v[88:89], off
	global_load_dword v232, v[88:89], off
	global_load_dword v232, v[88:89], off
	global_load_dword v232, v[88:89], off
	global_load_dword v232, v[88:89], off
	global_load_dword v232, v[88:89], off
	v_lshl_add_u64 v[90:91], s[0:1], 0, v[10:11]
	s_lshl_b32 s7, s13, 12
	s_lshl_b32 s23, s22, 9
	s_lshl_b32 s25, s24, 9
	s_lshl_b32 s27, s26, 9
	s_lshl_b32 s29, s28, 9
	s_lshl_b32 s31, s30, 9
	s_lshl_b32 s34, s33, 9
	s_lshl_b32 s36, s35, 9
	v_lshl_add_u64 v[92:93], v[2:3], 0, v[12:13]
	s_lshl_b32 s37, s96, 2
	s_lshl_b32 s38, s96, 6
	s_brev_b32 s6, 60
	s_mov_b32 s8, 0x358637bd
	s_mov_b32 s39, 0x800000
	s_mov_b32 s40, 0
	s_mov_b32 s42, s88
	s_branch .LBB0_624
.LBB0_623:
	s_waitcnt lgkmcnt(0)
	s_barrier
	v_lshl_add_u32 v142, v111, 2, s43
	v_add_u32_e32 v4, s7, v142
	v_add_u32_e32 v5, s23, v142
	ds_read_b64 v[130:131], v4
	ds_read_b64 v[132:133], v5
	v_add_u32_e32 v6, s25, v142
	v_add_u32_e32 v4, s27, v142
	ds_read_b64 v[134:135], v6
	ds_read_b64 v[8:9], v4
	s_waitcnt lgkmcnt(3)
	v_pk_mul_f32 v[4:5], v[130:131], v[130:131]
	s_waitcnt lgkmcnt(2)
	v_pk_mul_f32 v[6:7], v[132:133], v[132:133]
	v_mov_b32_e32 v137, v4
	v_mov_b32_e32 v136, v6
	v_mov_b32_e32 v4, v7
	v_pk_add_f32 v[4:5], v[136:137], v[4:5]
	ds_bpermute_b32 v137, v113, v5
	ds_bpermute_b32 v136, v113, v4
	v_lshlrev_b32_e32 v128, 16, v126
	v_and_b32_e32 v129, 0xffff0000, v126
	v_lshlrev_b32_e32 v126, 16, v125
	v_and_b32_e32 v127, 0xffff0000, v125
	s_waitcnt lgkmcnt(0)
	v_pk_add_f32 v[4:5], v[4:5], v[136:137]
	ds_bpermute_b32 v137, v114, v5
	ds_bpermute_b32 v136, v114, v4
	v_mul_f32_e32 v125, 0xbfb8aa3b, v128
	v_mul_f32_e32 v140, 0xbfb8aa3b, v129
	v_exp_f32_e32 v125, v125
	s_ashr_i32 s0, s42, 9
	s_waitcnt lgkmcnt(0)
	v_pk_add_f32 v[136:137], v[4:5], v[136:137]
	ds_bpermute_b32 v139, v115, v137
	ds_bpermute_b32 v138, v115, v136
	v_exp_f32_e32 v140, v140
	s_and_b32 s4, s15, 0x780
	s_ashr_i32 s1, s0, 31
	s_and_b32 s42, s14, 0x7c0
	s_waitcnt lgkmcnt(0)
	v_pk_add_f32 v[136:137], v[136:137], v[138:139]
	ds_bpermute_b32 v139, v116, v137
	ds_bpermute_b32 v138, v116, v136
	v_mov_b64_e32 v[6:7], s[8:9]
	s_lshl_b32 s4, s4, 1
	s_lshl_b64 s[14:15], s[0:1], 11
	v_mul_f32_e32 v141, 0xbfb8aa3b, v126
	s_waitcnt lgkmcnt(0)
	v_pk_add_f32 v[136:137], v[136:137], v[138:139]
	ds_bpermute_b32 v139, v117, v137
	ds_bpermute_b32 v138, v117, v136
	v_lshl_add_u64 v[4:5], v[90:91], 0, s[4:5]
	s_or_b32 s4, s14, s42
	v_add_f32_e32 v125, 1.0, v125
	v_exp_f32_e32 v144, v141
	s_waitcnt lgkmcnt(0)
	v_pk_add_f32 v[136:137], v[136:137], v[138:139]
	ds_bpermute_b32 v139, v118, v137
	ds_bpermute_b32 v138, v118, v136
	s_add_u32 s0, s4, s16
	v_add_f32_e32 v141, 1.0, v140
	v_rcp_f32_e32 v140, v125
	s_addc_u32 s1, s15, 0
	s_waitcnt lgkmcnt(0)
	v_pk_add_f32 v[136:137], v[136:137], v[138:139]
	s_lshl_b64 s[42:43], s[0:1], 13
	v_pk_fma_f32 v[136:137], v[136:137], s[6:7], v[6:7] op_sel_hi:[1,0,0]
	v_rcp_f32_e32 v141, v141
	v_mul_f32_e32 v125, 0x4b800000, v137
	v_cmp_gt_f32_e32 vcc, s39, v137
	v_mul_f32_e32 v138, 0x4b800000, v136
	v_cmp_gt_f32_e64 s[0:1], s39, v136
	v_cndmask_b32_e32 v125, v137, v125, vcc
	v_rsq_f32_e32 v125, v125
	v_cndmask_b32_e64 v136, v136, v138, s[0:1]
	v_rsq_f32_e32 v139, v136
	v_mul_f32_e32 v143, 0xbfb8aa3b, v127
	v_mul_f32_e32 v138, 0x45800000, v125
	v_cndmask_b32_e32 v138, v125, v138, vcc
	v_pk_mul_f32 v[130:131], v[130:131], v[138:139] op_sel_hi:[1,0]
	v_pk_mul_f32 v[128:129], v[140:141], v[128:129]
	v_exp_f32_e32 v143, v143
	v_lshl_add_u64 v[136:137], v[4:5], 0, s[42:43]
	v_mul_f32_e32 v140, 0x45800000, v139
	s_mov_b32 s14, s41
	s_mov_b32 s42, s10
	v_pk_mul_f32 v[130:131], v[222:223], v[130:131]
	s_nop 0
	v_pk_mul_f32 v[128:129], v[128:129], v[130:131]
	s_nop 0
	v_cvt_pk_bf16_f32 v125, v128, v129
	global_store_dword v[136:137], v125, off
	v_cndmask_b32_e64 v128, v139, v140, s[0:1]
	v_pk_mul_f32 v[136:137], v[134:135], v[134:135]
	v_pk_mul_f32 v[138:139], v[8:9], v[8:9]
	v_add_f32_e32 v125, 1.0, v144
	v_mov_b32_e32 v140, v138
	v_mov_b32_e32 v141, v136
	v_mov_b32_e32 v136, v139
	v_rcp_f32_e32 v130, v125
	v_add_f32_e32 v125, 1.0, v143
	v_pk_add_f32 v[136:137], v[140:141], v[136:137]
	v_rcp_f32_e32 v131, v125
	ds_bpermute_b32 v139, v113, v137
	ds_bpermute_b32 v138, v113, v136
	v_pk_mul_f32 v[128:129], v[132:133], v[128:129] op_sel_hi:[1,0]
	v_pk_mul_f32 v[126:127], v[130:131], v[126:127]
	v_pk_mul_f32 v[128:129], v[222:223], v[128:129]
	s_add_u32 s0, s4, s22
	v_pk_mul_f32 v[126:127], v[126:127], v[128:129]
	s_waitcnt lgkmcnt(0)
	v_pk_add_f32 v[128:129], v[136:137], v[138:139]
	ds_bpermute_b32 v131, v114, v129
	ds_bpermute_b32 v130, v114, v128
	v_cvt_pk_bf16_f32 v125, v126, v127
	s_addc_u32 s1, s15, 0
	s_lshl_b64 s[0:1], s[0:1], 13
	s_waitcnt lgkmcnt(0)
	v_pk_add_f32 v[126:127], v[128:129], v[130:131]
	ds_bpermute_b32 v129, v115, v127
	ds_bpermute_b32 v128, v115, v126
	v_lshl_add_u64 v[130:131], v[4:5], 0, s[0:1]
	global_store_dword v[130:131], v125, off
	v_lshlrev_b32_e32 v130, 16, v124
	v_and_b32_e32 v131, 0xffff0000, v124
	s_waitcnt lgkmcnt(0)
	v_pk_add_f32 v[124:125], v[126:127], v[128:129]
	ds_bpermute_b32 v127, v116, v125
	ds_bpermute_b32 v126, v116, v124
	v_mul_f32_e32 v128, 0xbfb8aa3b, v130
	v_mul_f32_e32 v129, 0xbfb8aa3b, v131
	v_exp_f32_e32 v128, v128
	v_exp_f32_e32 v129, v129
	s_waitcnt lgkmcnt(0)
	v_pk_add_f32 v[124:125], v[124:125], v[126:127]
	ds_bpermute_b32 v127, v117, v125
	ds_bpermute_b32 v126, v117, v124
	v_add_f32_e32 v128, 1.0, v128
	v_add_f32_e32 v129, 1.0, v129
	v_rcp_f32_e32 v128, v128
	v_rcp_f32_e32 v129, v129
	s_waitcnt lgkmcnt(0)
	v_pk_add_f32 v[124:125], v[124:125], v[126:127]
	ds_bpermute_b32 v127, v118, v125
	ds_bpermute_b32 v126, v118, v124
	v_pk_mul_f32 v[128:129], v[128:129], v[130:131]
	v_lshlrev_b32_e32 v130, 16, v123
	v_and_b32_e32 v131, 0xffff0000, v123
	s_add_u32 s0, s4, s24
	s_waitcnt lgkmcnt(0)
	v_pk_add_f32 v[124:125], v[124:125], v[126:127]
	s_addc_u32 s1, s15, 0
	v_pk_fma_f32 v[124:125], v[124:125], s[6:7], v[6:7] op_sel_hi:[1,0,0]
	s_lshl_b64 s[0:1], s[0:1], 13
	v_mul_f32_e32 v126, 0x4b800000, v125
	v_cmp_gt_f32_e32 vcc, s39, v125
	s_nop 1
	v_cndmask_b32_e32 v125, v125, v126, vcc
	v_rsq_f32_e32 v125, v125
	v_lshl_add_u64 v[126:127], v[4:5], 0, s[0:1]
	s_add_u32 s0, s4, s26
	s_addc_u32 s1, s15, 0
	v_mul_f32_e32 v123, 0x45800000, v125
	v_cndmask_b32_e32 v132, v125, v123, vcc
	v_pk_mul_f32 v[132:133], v[134:135], v[132:133] op_sel_hi:[1,0]
	v_mul_f32_e32 v123, 0x4b800000, v124
	v_pk_mul_f32 v[132:133], v[222:223], v[132:133]
	v_cmp_gt_f32_e32 vcc, s39, v124
	s_lshl_b64 s[0:1], s[0:1], 13
	s_nop 0
	v_cndmask_b32_e32 v123, v124, v123, vcc
	v_pk_mul_f32 v[124:125], v[128:129], v[132:133]
	v_rsq_f32_e32 v123, v123
	v_cvt_pk_bf16_f32 v124, v124, v125
	v_mul_f32_e32 v125, 0xbfb8aa3b, v130
	global_store_dword v[126:127], v124, off
	v_exp_f32_e32 v125, v125
	v_mul_f32_e32 v126, 0xbfb8aa3b, v131
	v_exp_f32_e32 v127, v126
	v_mul_f32_e32 v124, 0x45800000, v123
	v_cndmask_b32_e32 v124, v123, v124, vcc
	v_add_f32_e32 v123, 1.0, v125
	v_rcp_f32_e32 v126, v123
	v_add_f32_e32 v123, 1.0, v127
	v_rcp_f32_e32 v127, v123
	v_add_u32_e32 v123, s29, v142
	v_add_u32_e32 v125, s31, v142
	ds_read_b64 v[128:129], v123
	ds_read_b64 v[132:133], v125
	v_add_u32_e32 v123, s34, v142
	v_add_u32_e32 v125, s36, v142
	v_pk_mul_f32 v[8:9], v[8:9], v[124:125] op_sel_hi:[1,0]
	s_waitcnt lgkmcnt(1)
	v_pk_mul_f32 v[138:139], v[128:129], v[128:129]
	s_waitcnt lgkmcnt(0)
	v_pk_mul_f32 v[140:141], v[132:133], v[132:133]
	v_mov_b32_e32 v143, v138
	v_mov_b32_e32 v142, v140
	v_mov_b32_e32 v138, v141
	v_pk_add_f32 v[138:139], v[142:143], v[138:139]
	ds_bpermute_b32 v141, v113, v139
	ds_bpermute_b32 v140, v113, v138
	ds_read_b64 v[134:135], v123
	ds_read_b64 v[136:137], v125
	v_pk_mul_f32 v[8:9], v[222:223], v[8:9]
	v_pk_mul_f32 v[124:125], v[126:127], v[130:131]
	s_nop 0
	v_pk_mul_f32 v[8:9], v[124:125], v[8:9]
	s_waitcnt lgkmcnt(2)
	v_pk_add_f32 v[124:125], v[138:139], v[140:141]
	ds_bpermute_b32 v127, v114, v125
	ds_bpermute_b32 v126, v114, v124
	v_cvt_pk_bf16_f32 v123, v8, v9
	s_waitcnt lgkmcnt(0)
	v_pk_add_f32 v[8:9], v[124:125], v[126:127]
	ds_bpermute_b32 v125, v115, v9
	ds_bpermute_b32 v124, v115, v8
	v_lshl_add_u64 v[126:127], v[4:5], 0, s[0:1]
	global_store_dword v[126:127], v123, off
	v_lshlrev_b32_e32 v126, 16, v122
	v_and_b32_e32 v127, 0xffff0000, v122
	s_waitcnt lgkmcnt(0)
	v_pk_add_f32 v[8:9], v[8:9], v[124:125]
	ds_bpermute_b32 v123, v116, v9
	ds_bpermute_b32 v122, v116, v8
	v_mul_f32_e32 v124, 0xbfb8aa3b, v126
	v_mul_f32_e32 v125, 0xbfb8aa3b, v127
	v_exp_f32_e32 v124, v124
	v_exp_f32_e32 v125, v125
	s_waitcnt lgkmcnt(0)
	v_pk_add_f32 v[8:9], v[8:9], v[122:123]
	ds_bpermute_b32 v123, v117, v9
	ds_bpermute_b32 v122, v117, v8
	v_add_f32_e32 v124, 1.0, v124
	v_add_f32_e32 v125, 1.0, v125
	v_rcp_f32_e32 v124, v124
	v_rcp_f32_e32 v125, v125
	s_waitcnt lgkmcnt(0)
	v_pk_add_f32 v[8:9], v[8:9], v[122:123]
	ds_bpermute_b32 v123, v118, v9
	ds_bpermute_b32 v122, v118, v8
	v_pk_mul_f32 v[124:125], v[124:125], v[126:127]
	v_lshlrev_b32_e32 v126, 16, v121
	v_and_b32_e32 v127, 0xffff0000, v121
	s_add_u32 s0, s4, s28
	s_waitcnt lgkmcnt(0)
	v_pk_add_f32 v[8:9], v[8:9], v[122:123]
	s_addc_u32 s1, s15, 0
	v_pk_fma_f32 v[8:9], v[8:9], s[6:7], v[6:7] op_sel_hi:[1,0,0]
	s_lshl_b64 s[0:1], s[0:1], 13
	v_mul_f32_e32 v122, 0x4b800000, v9
	v_cmp_gt_f32_e32 vcc, s39, v9
	s_nop 1
	v_cndmask_b32_e32 v9, v9, v122, vcc
	v_rsq_f32_e32 v9, v9
	v_lshl_add_u64 v[122:123], v[4:5], 0, s[0:1]
	s_add_u32 s0, s4, s30
	s_addc_u32 s1, s15, 0
	v_mul_f32_e32 v121, 0x45800000, v9
	v_cndmask_b32_e32 v130, v9, v121, vcc
	v_pk_mul_f32 v[128:129], v[128:129], v[130:131] op_sel_hi:[1,0]
	v_mul_f32_e32 v9, 0x4b800000, v8
	v_cmp_gt_f32_e32 vcc, s39, v8
	v_pk_mul_f32 v[128:129], v[222:223], v[128:129]
	s_lshl_b64 s[0:1], s[0:1], 13
	v_cndmask_b32_e32 v8, v8, v9, vcc
	v_rsq_f32_e32 v121, v8
	v_pk_mul_f32 v[8:9], v[124:125], v[128:129]
	v_pk_mul_f32 v[124:125], v[134:135], v[134:135]
	v_cvt_pk_bf16_f32 v8, v8, v9
	v_mul_f32_e32 v9, 0xbfb8aa3b, v126
	global_store_dword v[122:123], v8, off
	v_exp_f32_e32 v9, v9
	v_mul_f32_e32 v122, 0xbfb8aa3b, v127
	v_exp_f32_e32 v123, v122
	v_pk_mul_f32 v[128:129], v[136:137], v[136:137]
	v_add_f32_e32 v9, 1.0, v9
	v_mov_b32_e32 v130, v128
	v_mov_b32_e32 v131, v124
	v_mov_b32_e32 v124, v129
	v_rcp_f32_e32 v122, v9
	v_add_f32_e32 v9, 1.0, v123
	v_pk_add_f32 v[124:125], v[130:131], v[124:125]
	v_rcp_f32_e32 v123, v9
	ds_bpermute_b32 v129, v113, v125
	ds_bpermute_b32 v128, v113, v124
	v_mul_f32_e32 v8, 0x45800000, v121
	v_cndmask_b32_e32 v8, v121, v8, vcc
	v_pk_mul_f32 v[8:9], v[132:133], v[8:9] op_sel_hi:[1,0]
	v_pk_mul_f32 v[122:123], v[122:123], v[126:127]
	v_pk_mul_f32 v[8:9], v[222:223], v[8:9]
	v_pk_mul_f32 v[8:9], v[122:123], v[8:9]
	s_waitcnt lgkmcnt(0)
	v_pk_add_f32 v[122:123], v[124:125], v[128:129]
	ds_bpermute_b32 v125, v114, v123
	ds_bpermute_b32 v124, v114, v122
	v_cvt_pk_bf16_f32 v121, v8, v9
	s_waitcnt lgkmcnt(0)
	v_pk_add_f32 v[8:9], v[122:123], v[124:125]
	ds_bpermute_b32 v123, v115, v9
	ds_bpermute_b32 v122, v115, v8
	v_lshl_add_u64 v[124:125], v[4:5], 0, s[0:1]
	global_store_dword v[124:125], v121, off
	v_lshlrev_b32_e32 v124, 16, v120
	v_and_b32_e32 v125, 0xffff0000, v120
	s_waitcnt lgkmcnt(0)
	v_pk_add_f32 v[8:9], v[8:9], v[122:123]
	ds_bpermute_b32 v121, v116, v9
	ds_bpermute_b32 v120, v116, v8
	v_mul_f32_e32 v122, 0xbfb8aa3b, v124
	v_mul_f32_e32 v123, 0xbfb8aa3b, v125
	v_exp_f32_e32 v122, v122
	v_exp_f32_e32 v123, v123
	s_waitcnt lgkmcnt(0)
	v_pk_add_f32 v[8:9], v[8:9], v[120:121]
	ds_bpermute_b32 v121, v117, v9
	ds_bpermute_b32 v120, v117, v8
	v_add_f32_e32 v122, 1.0, v122
	v_add_f32_e32 v123, 1.0, v123
	v_rcp_f32_e32 v122, v122
	v_rcp_f32_e32 v123, v123
	s_waitcnt lgkmcnt(0)
	v_pk_add_f32 v[8:9], v[8:9], v[120:121]
	ds_bpermute_b32 v121, v118, v9
	ds_bpermute_b32 v120, v118, v8
	v_pk_mul_f32 v[122:123], v[122:123], v[124:125]
	s_add_u32 s0, s4, s33
	s_addc_u32 s1, s15, 0
	s_lshl_b64 s[0:1], s[0:1], 13
	s_waitcnt lgkmcnt(0)
	v_pk_add_f32 v[8:9], v[8:9], v[120:121]
	v_lshlrev_b32_e32 v120, 16, v119
	v_pk_fma_f32 v[6:7], v[8:9], s[6:7], v[6:7] op_sel_hi:[1,0,0]
	v_and_b32_e32 v121, 0xffff0000, v119
	v_mul_f32_e32 v8, 0x4b800000, v7
	v_cmp_gt_f32_e32 vcc, s39, v7
	s_nop 1
	v_cndmask_b32_e32 v7, v7, v8, vcc
	v_rsq_f32_e32 v7, v7
	v_lshl_add_u64 v[8:9], v[4:5], 0, s[0:1]
	s_add_u32 s0, s4, s35
	s_addc_u32 s1, s15, 0
	v_mul_f32_e32 v119, 0x45800000, v7
	v_cndmask_b32_e32 v124, v7, v119, vcc
	v_pk_mul_f32 v[124:125], v[134:135], v[124:125] op_sel_hi:[1,0]
	v_cmp_gt_f32_e32 vcc, s39, v6
	v_pk_mul_f32 v[124:125], v[222:223], v[124:125]
	s_lshl_b64 s[0:1], s[0:1], 13
	v_pk_mul_f32 v[122:123], v[122:123], v[124:125]
	s_xor_b32 s40, s40, 1
	v_cvt_pk_bf16_f32 v7, v122, v123
	global_store_dword v[8:9], v7, off
	v_mul_f32_e32 v7, 0x4b800000, v6
	v_cndmask_b32_e32 v6, v6, v7, vcc
	v_rsq_f32_e32 v8, v6
	v_mul_f32_e32 v6, 0xbfb8aa3b, v120
	v_mul_f32_e32 v7, 0xbfb8aa3b, v121
	v_exp_f32_e32 v6, v6
	v_exp_f32_e32 v7, v7
	v_mul_f32_e32 v9, 0x45800000, v8
	v_cndmask_b32_e32 v8, v8, v9, vcc
	v_add_f32_e32 v6, 1.0, v6
	v_add_f32_e32 v7, 1.0, v7
	v_rcp_f32_e32 v6, v6
	v_rcp_f32_e32 v7, v7
	v_pk_mul_f32 v[8:9], v[136:137], v[8:9] op_sel_hi:[1,0]
	s_andn2_b64 vcc, exec, s[12:13]
	v_pk_mul_f32 v[2:3], v[222:223], v[8:9]
	v_pk_mul_f32 v[6:7], v[6:7], v[120:121]
	s_mov_b32 s15, s11
	v_pk_mul_f32 v[2:3], v[6:7], v[2:3]
	v_cvt_pk_bf16_f32 v6, v2, v3
	v_lshl_add_u64 v[2:3], v[4:5], 0, s[0:1]
	global_store_dword v[2:3], v6, off
	s_cbranch_vccz .LBB0_628
.LBB0_624:
	s_waitcnt vmcnt(45)
	v_mfma_f32_32x32x16_bf16 v[2:17], v[18:21], v[26:29], 0
	s_lshl_b32 s0, s40, 15
	s_add_i32 s43, s0, 0
	s_add_i32 s0, s43, s20
	s_add_i32 s0, s21, s0
	s_add_i32 s10, s42, s96
	s_waitcnt vmcnt(31)
	v_lshlrev_b32_e32 v127, 16, v95
	s_waitcnt vmcnt(30)
	v_lshlrev_b32_e32 v128, 16, v96
	v_mfma_f32_32x32x16_bf16 v[2:17], v[22:25], v[30:33], v[2:17]
	v_lshlrev_b32_e32 v143, 2, v1
	s_cmpk_gt_i32 s10, 0x7ff
	s_waitcnt vmcnt(29)
	v_lshlrev_b32_e32 v129, 16, v97
	s_waitcnt vmcnt(28)
	v_lshlrev_b32_e32 v130, 16, v98
	s_waitcnt vmcnt(27)
	v_lshlrev_b32_e32 v131, 16, v99
	s_waitcnt vmcnt(26)
	v_lshlrev_b32_e32 v132, 16, v100
	s_waitcnt vmcnt(25)
	v_lshlrev_b32_e32 v133, 16, v101
	v_mfma_f32_32x32x16_bf16 v[2:17], v[34:37], v[42:45], v[2:17]
	s_waitcnt vmcnt(24)
	v_lshlrev_b32_e32 v134, 16, v102
	s_waitcnt vmcnt(23)
	v_lshlrev_b32_e32 v135, 16, v103
	s_waitcnt vmcnt(22)
	v_lshlrev_b32_e32 v136, 16, v104
	s_waitcnt vmcnt(21)
	v_lshlrev_b32_e32 v137, 16, v105
	s_waitcnt vmcnt(20)
	v_lshlrev_b32_e32 v138, 16, v106
	s_waitcnt vmcnt(19)
	v_lshlrev_b32_e32 v139, 16, v107
	s_waitcnt vmcnt(18)
	v_lshlrev_b32_e32 v140, 16, v108
	v_mfma_f32_32x32x16_bf16 v[2:17], v[38:41], v[46:49], v[2:17]
	s_waitcnt vmcnt(17)
	v_lshlrev_b32_e32 v141, 16, v109
	s_waitcnt vmcnt(16)
	v_lshlrev_b32_e32 v142, 16, v110
	v_add3_u32 v143, s0, v112, v143
	s_cselect_b64 s[12:13], -1, 0
	s_cmpk_lt_i32 s10, 0x800
	s_mov_b64 s[0:1], -1
	v_mfma_f32_32x32x16_bf16 v[2:17], v[50:53], v[58:61], v[2:17]
	v_mfma_f32_32x32x16_bf16 v[2:17], v[54:57], v[62:65], v[2:17]
	v_mfma_f32_32x32x16_bf16 v[2:17], v[66:69], v[74:77], v[2:17]
	v_mfma_f32_32x32x16_bf16 v[2:17], v[70:73], v[78:81], v[2:17]
	s_nop 11
	v_add_f32_e32 v2, v2, v127
	v_add_f32_e32 v3, v3, v128
	v_add_f32_e32 v4, v4, v129
	v_add_f32_e32 v5, v5, v130
	v_add_f32_e32 v6, v6, v131
	v_add_f32_e32 v7, v7, v132
	v_add_f32_e32 v8, v8, v133
	v_add_f32_e32 v9, v9, v134
	v_add_f32_e32 v10, v10, v135
	v_add_f32_e32 v11, v11, v136
	v_add_f32_e32 v12, v12, v137
	v_add_f32_e32 v13, v13, v138
	v_add_f32_e32 v14, v14, v139
	v_add_f32_e32 v15, v15, v140
	v_add_f32_e32 v16, v16, v141
	v_add_f32_e32 v17, v17, v142
	ds_write2st64_b32 v143, v2, v3 offset1:2
	ds_write2st64_b32 v143, v4, v5 offset0:4 offset1:6
	ds_write2st64_b32 v143, v6, v7 offset0:16 offset1:18
	ds_write2st64_b32 v143, v8, v9 offset0:20 offset1:22
	ds_write2st64_b32 v143, v10, v11 offset0:32 offset1:34
	ds_write2st64_b32 v143, v12, v13 offset0:36 offset1:38
	ds_write2st64_b32 v143, v14, v15 offset0:48 offset1:50
	ds_write2st64_b32 v143, v16, v17 offset0:52 offset1:54
	s_cbranch_scc1 .LBB0_626
	s_add_i32 s11, s15, s37
	s_add_i32 s41, s14, s38
	s_mov_b64 s[0:1], 0
.LBB0_626:
	s_andn2_b64 vcc, exec, s[0:1]
	s_waitcnt vmcnt(7)
	v_mov_b32_e32 v126, v224
	v_mov_b32_e32 v125, v225
	v_mov_b32_e32 v124, v226
	v_mov_b32_e32 v123, v227
	v_mov_b32_e32 v122, v228
	v_mov_b32_e32 v121, v229
	v_mov_b32_e32 v120, v230
	v_mov_b32_e32 v119, v231
	s_cbranch_vccnz .LBB0_623
	s_ashr_i32 s0, s10, 9
	s_add_i32 s41, s38, s14
	s_ashr_i32 s11, s10, 31
	s_ashr_i32 s1, s0, 31
	s_and_b32 s4, s41, 0x7c0
	s_lshl_b64 s[44:45], s[10:11], 14
	s_lshl_b64 s[46:47], s[10:11], 15
	v_lshl_add_u64 v[2:3], v[82:83], 0, s[44:45]
	v_lshl_add_u64 v[4:5], v[84:85], 0, s[46:47]
	s_lshl_b64 s[0:1], s[0:1], 11
	s_add_i32 s4, s4, s16
	global_load_dwordx4 v[18:21], v[2:3], off
	global_load_dwordx4 v[22:25], v[2:3], off offset:32
	global_load_dwordx4 v[26:29], v[4:5], off
	global_load_dwordx4 v[30:33], v[4:5], off offset:1024
	global_load_dwordx4 v[34:37], v[2:3], off offset:64
	global_load_dwordx4 v[38:41], v[2:3], off offset:96
	global_load_dwordx4 v[42:45], v[4:5], off offset:2048
	global_load_dwordx4 v[46:49], v[4:5], off offset:3072
	v_add_co_u32_e32 v4, vcc, s9, v4
	s_add_u32 s0, s0, s4
	s_nop 0
	v_addc_co_u32_e32 v5, vcc, 0, v5, vcc
	global_load_dwordx4 v[50:53], v[2:3], off offset:128
	global_load_dwordx4 v[54:57], v[2:3], off offset:160
	global_load_dwordx4 v[58:61], v[4:5], off
	global_load_dwordx4 v[62:65], v[4:5], off offset:1024
	global_load_dwordx4 v[66:69], v[2:3], off offset:192
	global_load_dwordx4 v[70:73], v[2:3], off offset:224
	global_load_dwordx4 v[74:77], v[4:5], off offset:2048
	global_load_dwordx4 v[78:81], v[4:5], off offset:3072
	v_lshl_add_u64 v[2:3], v[92:93], 0, s[44:45]
	s_addc_u32 s1, s1, 0
	s_add_i32 s11, s37, s15
	global_load_ushort v95, v[2:3], off
	global_load_ushort v96, v[2:3], off offset:256
	global_load_ushort v97, v[2:3], off offset:512
	global_load_ushort v98, v[2:3], off offset:768
	global_load_ushort v99, v[2:3], off offset:2048
	global_load_ushort v100, v[2:3], off offset:2304
	global_load_ushort v101, v[2:3], off offset:2560
	global_load_ushort v102, v[2:3], off offset:2816
	v_add_co_u32_e32 v2, vcc, s9, v2
	s_and_b32 s4, s11, 0x780
	s_nop 0
	v_addc_co_u32_e32 v3, vcc, 0, v3, vcc
	s_lshl_b32 s4, s4, 1
	global_load_ushort v103, v[2:3], off
	global_load_ushort v104, v[2:3], off offset:256
	global_load_ushort v105, v[2:3], off offset:512
	global_load_ushort v106, v[2:3], off offset:768
	global_load_ushort v107, v[2:3], off offset:2048
	global_load_ushort v108, v[2:3], off offset:2304
	global_load_ushort v109, v[2:3], off offset:2560
	global_load_ushort v110, v[2:3], off offset:2816
	v_lshl_add_u64 v[2:3], v[86:87], 0, s[4:5]
	s_mul_i32 s4, s1, 0x6800
	v_mad_u64_u32 v[2:3], s[0:1], s0, v94, v[2:3]
	v_add_u32_e32 v3, s4, v3
	v_add_co_u32_e32 v4, vcc, s17, v2
	s_nop 1
	v_addc_co_u32_e32 v5, vcc, 0, v3, vcc
	v_add_co_u32_e32 v6, vcc, s18, v2
	s_nop 1
	v_addc_co_u32_e32 v7, vcc, 0, v3, vcc
	v_add_co_u32_e32 v8, vcc, s19, v2
	s_nop 1
	v_addc_co_u32_e32 v9, vcc, 0, v3, vcc
	v_add_co_u32_e32 v14, vcc, 0x1a000, v2
	s_nop 1
	v_addc_co_u32_e32 v15, vcc, 0, v3, vcc
	v_add_co_u32_e32 v16, vcc, 0x20000, v2
	s_nop 1
	v_addc_co_u32_e32 v17, vcc, 0, v3, vcc
	v_add_co_u32_e32 v128, vcc, 0x27000, v2
	s_nop 1
	v_addc_co_u32_e32 v129, vcc, 0, v3, vcc
	v_add_co_u32_e32 v130, vcc, 0x2d000, v2
	s_nop 1
	v_addc_co_u32_e32 v131, vcc, 0, v3, vcc
	global_load_dword v224, v[2:3], off
	global_load_dword v225, v[4:5], off offset:2048
	global_load_dword v226, v[6:7], off
	global_load_dword v227, v[8:9], off offset:2048
	s_nop 0
	global_load_dword v228, v[14:15], off
	s_nop 0
	global_load_dword v229, v[16:17], off offset:2048
	s_nop 0
	global_load_dword v230, v[128:129], off
	global_load_dword v231, v[130:131], off offset:2048
	s_branch .LBB0_623

.LBB0_1496:
	s_setprio 0
	s_cmpk_gt_i32 s88, 0x7ff
	s_waitcnt vmcnt(0) lgkmcnt(0)
	s_barrier
	s_cbranch_scc1 .LBB0_1503
	s_add_u32 s0, s94, 0x42503000
	s_addc_u32 s1, s95, 0
	v_readlane_b32 s23, v247, 0
	s_ashr_i32 s12, s88, 9
	s_lshl_b32 s16, s88, 6
	s_ashr_i32 s89, s88, 31
	s_lshr_b32 s4, s23, 7
	s_bfe_u32 s22, s23, 0x10006
	s_ashr_i32 s13, s12, 31
	s_and_b32 s17, s16, 0x7c0
	s_lshl_b64 s[14:15], s[88:89], 14
	s_add_u32 s8, s70, s14
	s_addc_u32 s9, s71, s15
	s_lshl_b32 s24, s22, 13
	v_lshl_or_b32 v2, v175, 8, s24
	v_mov_b32_e32 v3, 0
	v_lshl_add_u64 v[4:5], s[8:9], 0, v[2:3]
	s_lshl_b64 s[8:9], s[88:89], 15
	v_readlane_b32 s27, v246, 11
	s_mov_b32 s5, 0
	s_add_u32 s10, s27, s8
	v_readlane_b32 s28, v246, 19
	s_addc_u32 s11, s28, s9
	s_lshl_b64 s[8:9], s[4:5], 13
	v_lshlrev_b32_e32 v6, 4, v197
	v_mov_b32_e32 v7, v3
	s_add_u32 s10, s10, s8
	v_lshl_add_u64 v[4:5], v[4:5], 0, v[6:7]
	s_addc_u32 s11, s11, s9
	v_lshlrev_b32_e32 v8, 4, v162
	v_mov_b32_e32 v9, v3
	s_lshl_b64 s[12:13], s[12:13], 11
	v_readlane_b32 s25, v247, 37
	v_lshl_add_u64 v[10:11], s[10:11], 0, v[8:9]
	global_load_dwordx4 v[18:21], v[4:5], off
	global_load_dwordx4 v[22:25], v[4:5], off offset:32
	global_load_dwordx4 v[26:29], v8, s[10:11]
	global_load_dwordx4 v[30:33], v8, s[10:11] offset:1024
	global_load_dwordx4 v[34:37], v[4:5], off offset:64
	global_load_dwordx4 v[38:41], v[4:5], off offset:96
	global_load_dwordx4 v[42:45], v8, s[10:11] offset:2048
	global_load_dwordx4 v[46:49], v8, s[10:11] offset:3072
	s_add_u32 s10, s25, s14
	v_readlane_b32 s26, v247, 38
	s_addc_u32 s14, s26, s15
	s_add_u32 s10, s10, s24
	s_movk_i32 s11, 0x1000
	s_addc_u32 s15, s14, 0
	s_lshl_b32 s4, s4, 6
	v_add_co_u32_e32 v10, vcc, s11, v10
	s_add_u32 s14, s10, s4
	s_nop 0
	v_addc_co_u32_e32 v11, vcc, 0, v11, vcc
	global_load_dwordx4 v[50:53], v[4:5], off offset:128
	global_load_dwordx4 v[54:57], v[4:5], off offset:160
	global_load_dwordx4 v[58:61], v[10:11], off
	global_load_dwordx4 v[62:65], v[10:11], off offset:1024
	global_load_dwordx4 v[66:69], v[4:5], off offset:192
	global_load_dwordx4 v[70:73], v[4:5], off offset:224
	global_load_dwordx4 v[74:77], v[10:11], off offset:2048
	global_load_dwordx4 v[78:81], v[10:11], off offset:3072
	s_addc_u32 s15, s15, 0
	v_lshlrev_b32_e32 v4, 1, v175
	v_mov_b32_e32 v5, v3
	v_lshl_add_u64 v[10:11], s[14:15], 0, v[4:5]
	v_readlane_b32 s15, v247, 9
	v_lshlrev_b32_e32 v12, 10, v197
	v_mov_b32_e32 v13, v3
	s_or_b32 s10, s12, s17
	s_lshl_b32 s18, s15, 3
	v_lshl_add_u64 v[10:11], v[10:11], 0, v[12:13]
	s_add_u32 s10, s10, s18
	v_readlane_b32 s12, v247, 10
	global_load_ushort v94, v[10:11], off
	global_load_ushort v95, v[10:11], off offset:256
	global_load_ushort v96, v[10:11], off offset:512
	global_load_ushort v97, v[10:11], off offset:768
	global_load_ushort v98, v[10:11], off offset:2048
	global_load_ushort v99, v[10:11], off offset:2304
	global_load_ushort v100, v[10:11], off offset:2560
	global_load_ushort v101, v[10:11], off offset:2816
	v_add_co_u32_e32 v10, vcc, s11, v10
	s_addc_u32 s14, s13, 0
	s_lshl_b32 s17, s88, 2
	s_and_b32 s12, s12, 0xf00
	v_addc_co_u32_e32 v11, vcc, 0, v11, vcc
	s_add_u32 s12, s0, s12
	global_load_ushort v102, v[10:11], off
	global_load_ushort v103, v[10:11], off offset:256
	global_load_ushort v104, v[10:11], off offset:512
	global_load_ushort v105, v[10:11], off offset:768
	global_load_ushort v106, v[10:11], off offset:2048
	global_load_ushort v107, v[10:11], off offset:2304
	global_load_ushort v108, v[10:11], off offset:2560
	global_load_ushort v109, v[10:11], off offset:2816
	s_addc_u32 s13, s1, 0
	v_lshlrev_b32_e32 v10, 2, v162
	v_mov_b32_e32 v11, v3
	v_lshl_add_u64 v[14:15], s[12:13], 0, v[10:11]
	v_mov_b32_e32 v1, 0x7000
	s_movk_i32 s19, 0x7000
	s_mulk_i32 s14, 0x7000
	v_mad_u64_u32 v[14:15], s[12:13], s10, v1, v[14:15]
	v_add_u32_e32 v15, s14, v15
	v_add_co_u32_e32 v16, vcc, s19, v14
	s_mov_b32 s20, 0xe000
	s_nop 0
	v_addc_co_u32_e32 v17, vcc, 0, v15, vcc
	v_add_co_u32_e32 v82, vcc, s20, v14
	s_mov_b32 s21, 0x15000
	s_nop 0
	v_addc_co_u32_e32 v83, vcc, 0, v15, vcc
	v_add_co_u32_e32 v84, vcc, s21, v14
	s_mov_b32 s10, 0x1c000
	s_nop 0
	v_addc_co_u32_e32 v85, vcc, 0, v15, vcc
	v_add_co_u32_e32 v86, vcc, s10, v14
	s_mov_b32 s10, 0x23000
	s_nop 0
	v_addc_co_u32_e32 v87, vcc, 0, v15, vcc
	v_add_co_u32_e32 v88, vcc, s10, v14
	s_mov_b32 s10, 0x2a000
	s_nop 0
	v_addc_co_u32_e32 v89, vcc, 0, v15, vcc
	v_add_co_u32_e32 v90, vcc, s10, v14
	s_mov_b32 s10, 0x31000
	s_nop 0
	v_addc_co_u32_e32 v91, vcc, 0, v15, vcc
	v_add_co_u32_e32 v92, vcc, s10, v14
	s_lshl_b32 s22, s22, 14
	s_nop 0
	v_addc_co_u32_e32 v93, vcc, 0, v15, vcc
	global_load_dword v224, v[14:15], off
	global_load_dword v225, v[16:17], off
	global_load_dword v226, v[82:83], off
	global_load_dword v227, v[84:85], off
	global_load_dword v228, v[86:87], off
	global_load_dword v229, v[88:89], off
	global_load_dword v230, v[90:91], off
	global_load_dword v231, v[92:93], off
	s_and_b32 s23, s23, 0xffffff80
	s_add_u32 s8, s27, s8
	s_addc_u32 s9, s28, s9
	v_lshl_add_u64 v[84:85], s[8:9], 0, v[8:9]
	s_add_u32 s8, s25, s24
	s_addc_u32 s9, s26, 0
	s_add_u32 s8, s8, s4
	v_mov_b32_e32 v15, v3
	v_lshl_add_u64 v[2:3], s[70:71], 0, v[2:3]
	s_addc_u32 s9, s9, 0
	v_lshl_add_u64 v[82:83], v[2:3], 0, v[6:7]
	v_lshl_add_u64 v[2:3], s[8:9], 0, v[4:5]
	v_mbcnt_hi_u32_b32 v4, -1, v163
	v_and_b32_e32 v5, 64, v4
	v_add_u32_e32 v5, 64, v5
	v_xor_b32_e32 v6, 1, v4
	v_cmp_lt_i32_e32 vcc, v6, v5
	v_readlane_b32 s12, v247, 3
	v_readlane_b32 s13, v247, 4
	v_cndmask_b32_e32 v6, v4, v6, vcc
	v_lshlrev_b32_e32 v112, 2, v6
	v_xor_b32_e32 v6, 2, v4
	v_cmp_lt_i32_e32 vcc, v6, v5
	s_load_dwordx2 s[12:13], s[12:13], 0xa0
	v_lshl_add_u64 v[86:87], s[0:1], 0, v[10:11]
	v_cndmask_b32_e32 v6, v4, v6, vcc
	v_lshlrev_b32_e32 v113, 2, v6
	v_xor_b32_e32 v6, 4, v4
	v_cmp_lt_i32_e32 vcc, v6, v5
	v_readlane_b32 s0, v247, 47
	v_lshlrev_b32_e32 v14, 3, v162
	v_cndmask_b32_e32 v6, v4, v6, vcc
	v_lshlrev_b32_e32 v114, 2, v6
	v_xor_b32_e32 v6, 8, v4
	v_cmp_lt_i32_e32 vcc, v6, v5
	v_readlane_b32 s1, v247, 48
	s_or_b32 s24, s18, 1
	v_cndmask_b32_e32 v6, v4, v6, vcc
	v_lshlrev_b32_e32 v115, 2, v6
	v_xor_b32_e32 v6, 16, v4
	v_cmp_lt_i32_e32 vcc, v6, v5
	s_or_b32 s26, s18, 2
	s_or_b32 s28, s18, 3
	v_cndmask_b32_e32 v6, v4, v6, vcc
	v_lshlrev_b32_e32 v116, 2, v6
	v_xor_b32_e32 v6, 32, v4
	v_cmp_lt_i32_e32 vcc, v6, v5
	s_or_b32 s30, s18, 4
	s_or_b32 s33, s18, 5
	v_cndmask_b32_e32 v4, v4, v6, vcc
	s_or_b32 s35, s18, 6
	s_or_b32 s37, s18, 7
	v_lshlrev_b32_e32 v110, 1, v162
	v_lshlrev_b32_e32 v111, 11, v197
	v_lshlrev_b32_e32 v117, 2, v4
	s_waitcnt lgkmcnt(0)
	v_lshl_add_u64 v[88:89], s[12:13], 0, v[14:15]
	global_load_dwordx2 v[222:223], v[88:89], off
	global_load_dword v232, v[88:89], off
	global_load_dword v232, v[88:89], off
	global_load_dword v232, v[88:89], off
	global_load_dword v232, v[88:89], off
	global_load_dword v232, v[88:89], off
	global_load_dword v232, v[88:89], off
	global_load_dword v232, v[88:89], off
	v_lshl_add_u64 v[90:91], s[0:1], 0, v[10:11]
	s_lshl_b32 s9, s15, 12
	s_lshl_b32 s25, s24, 9
	s_lshl_b32 s27, s26, 9
	s_lshl_b32 s29, s28, 9
	s_lshl_b32 s31, s30, 9
	s_lshl_b32 s34, s33, 9
	s_lshl_b32 s36, s35, 9
	s_lshl_b32 s38, s37, 9
	v_lshl_add_u64 v[92:93], v[2:3], 0, v[12:13]
	s_lshl_b32 s39, s96, 2
	s_lshl_b32 s40, s96, 6
	s_brev_b32 s8, 60
	s_mov_b32 s10, 0x358637bd
	s_mov_b32 s41, 0x800000
	s_mov_b32 s42, 0
	s_mov_b32 s44, s88
	s_branch .LBB0_1499
.LBB0_1498:
	s_waitcnt lgkmcnt(0)
	s_barrier
	v_lshl_add_u32 v140, v110, 2, s45
	v_add_u32_e32 v4, s9, v140
	v_add_u32_e32 v5, s25, v140
	ds_read_b64 v[128:129], v4
	ds_read_b64 v[130:131], v5
	v_add_u32_e32 v6, s27, v140
	v_add_u32_e32 v4, s29, v140
	ds_read_b64 v[132:133], v6
	ds_read_b64 v[8:9], v4
	s_waitcnt lgkmcnt(3)
	v_pk_mul_f32 v[4:5], v[128:129], v[128:129]
	s_waitcnt lgkmcnt(2)
	v_pk_mul_f32 v[6:7], v[130:131], v[130:131]
	v_mov_b32_e32 v135, v4
	v_mov_b32_e32 v134, v6
	v_mov_b32_e32 v4, v7
	v_pk_add_f32 v[4:5], v[134:135], v[4:5]
	ds_bpermute_b32 v135, v112, v5
	ds_bpermute_b32 v134, v112, v4
	v_lshlrev_b32_e32 v126, 16, v125
	v_and_b32_e32 v127, 0xffff0000, v125
	v_lshlrev_b32_e32 v136, 16, v124
	v_and_b32_e32 v137, 0xffff0000, v124
	s_waitcnt lgkmcnt(0)
	v_pk_add_f32 v[4:5], v[4:5], v[134:135]
	ds_bpermute_b32 v125, v113, v5
	ds_bpermute_b32 v124, v113, v4
	s_ashr_i32 s0, s44, 9
	v_mul_f32_e32 v138, 0xbfb8aa3b, v126
	v_mul_f32_e32 v139, 0xbfb8aa3b, v127
	s_and_b32 s4, s17, 0x780
	s_waitcnt lgkmcnt(0)
	v_pk_add_f32 v[124:125], v[4:5], v[124:125]
	ds_bpermute_b32 v135, v114, v125
	ds_bpermute_b32 v134, v114, v124
	s_ashr_i32 s1, s0, 31
	v_exp_f32_e32 v138, v138
	v_exp_f32_e32 v139, v139
	s_and_b32 s44, s16, 0x7c0
	s_waitcnt lgkmcnt(0)
	v_pk_add_f32 v[124:125], v[124:125], v[134:135]
	ds_bpermute_b32 v135, v115, v125
	ds_bpermute_b32 v134, v115, v124
	v_mov_b64_e32 v[6:7], s[10:11]
	s_lshl_b32 s4, s4, 1
	s_lshl_b64 s[16:17], s[0:1], 11
	v_lshl_add_u64 v[4:5], v[90:91], 0, s[4:5]
	s_waitcnt lgkmcnt(0)
	v_pk_add_f32 v[124:125], v[124:125], v[134:135]
	ds_bpermute_b32 v135, v116, v125
	ds_bpermute_b32 v134, v116, v124
	s_or_b32 s4, s16, s44
	s_add_u32 s0, s4, s18
	s_addc_u32 s1, s17, 0
	v_add_f32_e32 v138, 1.0, v138
	s_waitcnt lgkmcnt(0)
	v_pk_add_f32 v[124:125], v[124:125], v[134:135]
	ds_bpermute_b32 v135, v117, v125
	ds_bpermute_b32 v134, v117, v124
	v_add_f32_e32 v139, 1.0, v139
	s_lshl_b64 s[44:45], s[0:1], 13
	v_rcp_f32_e32 v138, v138
	v_rcp_f32_e32 v139, v139
	s_waitcnt lgkmcnt(0)
	v_pk_add_f32 v[124:125], v[124:125], v[134:135]
	v_mul_f32_e32 v141, 0xbfb8aa3b, v136
	v_pk_fma_f32 v[124:125], v[124:125], s[8:9], v[6:7] op_sel_hi:[1,0,0]
	v_pk_mul_f32 v[126:127], v[138:139], v[126:127]
	v_mul_f32_e32 v134, 0x4b800000, v125
	v_cmp_gt_f32_e32 vcc, s41, v125
	v_mul_f32_e32 v135, 0x4b800000, v124
	v_cmp_gt_f32_e64 s[0:1], s41, v124
	v_cndmask_b32_e32 v125, v125, v134, vcc
	v_rsq_f32_e32 v134, v125
	v_cndmask_b32_e64 v124, v124, v135, s[0:1]
	v_rsq_f32_e32 v135, v124
	v_mul_f32_e32 v142, 0xbfb8aa3b, v137
	v_mul_f32_e32 v138, 0x45800000, v134
	v_cndmask_b32_e32 v134, v134, v138, vcc
	v_pk_mul_f32 v[128:129], v[128:129], v[134:135] op_sel_hi:[1,0]
	v_exp_f32_e32 v141, v141
	v_exp_f32_e32 v142, v142
	v_lshl_add_u64 v[124:125], v[4:5], 0, s[44:45]
	v_mul_f32_e32 v139, 0x45800000, v135
	s_mov_b32 s16, s43
	s_mov_b32 s44, s12
	v_pk_mul_f32 v[128:129], v[222:223], v[128:129]
	s_nop 0
	v_pk_mul_f32 v[126:127], v[126:127], v[128:129]
	v_pk_mul_f32 v[128:129], v[132:133], v[132:133]
	v_cvt_pk_bf16_f32 v126, v126, v127
	global_store_dword v[124:125], v126, off
	v_cndmask_b32_e64 v124, v135, v139, s[0:1]
	v_pk_mul_f32 v[134:135], v[8:9], v[8:9]
	v_add_f32_e32 v125, 1.0, v141
	v_mov_b32_e32 v138, v134
	v_mov_b32_e32 v139, v128
	v_mov_b32_e32 v128, v135
	v_rcp_f32_e32 v126, v125
	v_add_f32_e32 v125, 1.0, v142
	v_pk_add_f32 v[128:129], v[138:139], v[128:129]
	v_rcp_f32_e32 v127, v125
	ds_bpermute_b32 v135, v112, v129
	ds_bpermute_b32 v134, v112, v128
	v_pk_mul_f32 v[124:125], v[130:131], v[124:125] op_sel_hi:[1,0]
	v_pk_mul_f32 v[126:127], v[126:127], v[136:137]
	v_pk_mul_f32 v[124:125], v[222:223], v[124:125]
	s_add_u32 s0, s4, s24
	v_pk_mul_f32 v[124:125], v[126:127], v[124:125]
	s_waitcnt lgkmcnt(0)
	v_pk_add_f32 v[126:127], v[128:129], v[134:135]
	ds_bpermute_b32 v129, v113, v127
	ds_bpermute_b32 v128, v113, v126
	v_cvt_pk_bf16_f32 v130, v124, v125
	s_addc_u32 s1, s17, 0
	s_lshl_b64 s[0:1], s[0:1], 13
	v_add_u32_e32 v134, s38, v140
	s_waitcnt lgkmcnt(0)
	v_pk_add_f32 v[124:125], v[126:127], v[128:129]
	ds_bpermute_b32 v127, v114, v125
	ds_bpermute_b32 v126, v114, v124
	v_lshl_add_u64 v[128:129], v[4:5], 0, s[0:1]
	global_store_dword v[128:129], v130, off
	v_lshlrev_b32_e32 v128, 16, v123
	v_and_b32_e32 v129, 0xffff0000, v123
	s_waitcnt lgkmcnt(0)
	v_pk_add_f32 v[124:125], v[124:125], v[126:127]
	ds_bpermute_b32 v127, v115, v125
	ds_bpermute_b32 v126, v115, v124
	v_mul_f32_e32 v123, 0xbfb8aa3b, v128
	v_exp_f32_e32 v123, v123
	v_mul_f32_e32 v130, 0xbfb8aa3b, v129
	v_exp_f32_e32 v131, v130
	s_waitcnt lgkmcnt(0)
	v_pk_add_f32 v[124:125], v[124:125], v[126:127]
	ds_bpermute_b32 v127, v116, v125
	ds_bpermute_b32 v126, v116, v124
	v_add_f32_e32 v123, 1.0, v123
	v_rcp_f32_e32 v130, v123
	v_add_f32_e32 v123, 1.0, v131
	v_rcp_f32_e32 v131, v123
	s_waitcnt lgkmcnt(0)
	v_pk_add_f32 v[124:125], v[124:125], v[126:127]
	ds_bpermute_b32 v127, v117, v125
	ds_bpermute_b32 v126, v117, v124
	v_pk_mul_f32 v[128:129], v[130:131], v[128:129]
	v_lshlrev_b32_e32 v130, 16, v122
	v_and_b32_e32 v131, 0xffff0000, v122
	s_add_u32 s0, s4, s26
	s_waitcnt lgkmcnt(0)
	v_pk_add_f32 v[124:125], v[124:125], v[126:127]
	s_addc_u32 s1, s17, 0
	v_pk_fma_f32 v[124:125], v[124:125], s[8:9], v[6:7] op_sel_hi:[1,0,0]
	s_lshl_b64 s[0:1], s[0:1], 13
	v_mul_f32_e32 v123, 0x4b800000, v125
	v_cmp_gt_f32_e32 vcc, s41, v125
	v_lshl_add_u64 v[126:127], v[4:5], 0, s[0:1]
	s_add_u32 s0, s4, s28
	v_cndmask_b32_e32 v123, v125, v123, vcc
	v_rsq_f32_e32 v123, v123
	v_mul_f32_e32 v125, 0x4b800000, v124
	s_addc_u32 s1, s17, 0
	s_lshl_b64 s[0:1], s[0:1], 13
	v_mul_f32_e32 v122, 0x45800000, v123
	v_cndmask_b32_e32 v122, v123, v122, vcc
	v_pk_mul_f32 v[122:123], v[132:133], v[122:123] op_sel_hi:[1,0]
	v_cmp_gt_f32_e32 vcc, s41, v124
	v_pk_mul_f32 v[122:123], v[222:223], v[122:123]
	s_nop 0
	v_pk_mul_f32 v[122:123], v[128:129], v[122:123]
	v_cndmask_b32_e32 v124, v124, v125, vcc
	v_cvt_pk_bf16_f32 v122, v122, v123
	v_mul_f32_e32 v123, 0xbfb8aa3b, v130
	v_rsq_f32_e32 v124, v124
	v_exp_f32_e32 v123, v123
	v_mul_f32_e32 v125, 0xbfb8aa3b, v131
	v_exp_f32_e32 v125, v125
	global_store_dword v[126:127], v122, off
	v_mul_f32_e32 v122, 0x45800000, v124
	v_add_f32_e32 v123, 1.0, v123
	v_cndmask_b32_e32 v122, v124, v122, vcc
	v_rcp_f32_e32 v124, v123
	v_add_f32_e32 v123, 1.0, v125
	v_rcp_f32_e32 v125, v123
	v_add_u32_e32 v123, s31, v140
	v_add_u32_e32 v128, s34, v140
	ds_read_b64 v[126:127], v123
	ds_read_b64 v[128:129], v128
	v_add_u32_e32 v123, s36, v140
	v_pk_mul_f32 v[8:9], v[8:9], v[122:123] op_sel_hi:[1,0]
	ds_read_b64 v[132:133], v123
	ds_read_b64 v[134:135], v134
	s_waitcnt lgkmcnt(3)
	v_pk_mul_f32 v[136:137], v[126:127], v[126:127]
	s_waitcnt lgkmcnt(2)
	v_pk_mul_f32 v[138:139], v[128:129], v[128:129]
	v_mov_b32_e32 v141, v136
	v_mov_b32_e32 v140, v138
	v_mov_b32_e32 v136, v139
	v_pk_add_f32 v[136:137], v[140:141], v[136:137]
	ds_bpermute_b32 v139, v112, v137
	ds_bpermute_b32 v138, v112, v136
	v_pk_mul_f32 v[8:9], v[222:223], v[8:9]
	v_pk_mul_f32 v[122:123], v[124:125], v[130:131]
	s_nop 0
	v_pk_mul_f32 v[8:9], v[122:123], v[8:9]
	s_waitcnt lgkmcnt(0)
	v_pk_add_f32 v[122:123], v[136:137], v[138:139]
	ds_bpermute_b32 v125, v113, v123
	ds_bpermute_b32 v124, v113, v122
	v_cvt_pk_bf16_f32 v130, v8, v9
	s_waitcnt lgkmcnt(0)
	v_pk_add_f32 v[8:9], v[122:123], v[124:125]
	ds_bpermute_b32 v123, v114, v9
	ds_bpermute_b32 v122, v114, v8
	v_lshl_add_u64 v[124:125], v[4:5], 0, s[0:1]
	global_store_dword v[124:125], v130, off
	v_lshlrev_b32_e32 v124, 16, v121
	v_and_b32_e32 v125, 0xffff0000, v121
	s_waitcnt lgkmcnt(0)
	v_pk_add_f32 v[8:9], v[8:9], v[122:123]
	ds_bpermute_b32 v123, v115, v9
	ds_bpermute_b32 v122, v115, v8
	v_mul_f32_e32 v121, 0xbfb8aa3b, v124
	v_exp_f32_e32 v121, v121
	v_mul_f32_e32 v130, 0xbfb8aa3b, v125
	v_exp_f32_e32 v131, v130
	s_waitcnt lgkmcnt(0)
	v_pk_add_f32 v[8:9], v[8:9], v[122:123]
	ds_bpermute_b32 v123, v116, v9
	ds_bpermute_b32 v122, v116, v8
	v_add_f32_e32 v121, 1.0, v121
	v_rcp_f32_e32 v130, v121
	v_add_f32_e32 v121, 1.0, v131
	v_rcp_f32_e32 v131, v121
	s_waitcnt lgkmcnt(0)
	v_pk_add_f32 v[8:9], v[8:9], v[122:123]
	ds_bpermute_b32 v123, v117, v9
	ds_bpermute_b32 v122, v117, v8
	v_pk_mul_f32 v[124:125], v[130:131], v[124:125]
	v_lshlrev_b32_e32 v130, 16, v120
	v_and_b32_e32 v131, 0xffff0000, v120
	s_add_u32 s0, s4, s30
	s_waitcnt lgkmcnt(0)
	v_pk_add_f32 v[8:9], v[8:9], v[122:123]
	s_addc_u32 s1, s17, 0
	v_pk_fma_f32 v[8:9], v[8:9], s[8:9], v[6:7] op_sel_hi:[1,0,0]
	s_lshl_b64 s[0:1], s[0:1], 13
	v_mul_f32_e32 v121, 0x4b800000, v9
	v_cmp_gt_f32_e32 vcc, s41, v9
	v_lshl_add_u64 v[122:123], v[4:5], 0, s[0:1]
	s_add_u32 s0, s4, s33
	v_cndmask_b32_e32 v9, v9, v121, vcc
	v_rsq_f32_e32 v9, v9
	s_addc_u32 s1, s17, 0
	s_lshl_b64 s[0:1], s[0:1], 13
	v_mul_f32_e32 v120, 0x45800000, v9
	v_cndmask_b32_e32 v120, v9, v120, vcc
	v_pk_mul_f32 v[120:121], v[126:127], v[120:121] op_sel_hi:[1,0]
	v_mul_f32_e32 v9, 0x4b800000, v8
	v_cmp_gt_f32_e32 vcc, s41, v8
	v_pk_mul_f32 v[120:121], v[222:223], v[120:121]
	s_nop 0
	v_cndmask_b32_e32 v8, v8, v9, vcc
	v_rsq_f32_e32 v126, v8
	v_pk_mul_f32 v[8:9], v[124:125], v[120:121]
	v_mul_f32_e32 v120, 0xbfb8aa3b, v131
	v_cvt_pk_bf16_f32 v8, v8, v9
	v_mul_f32_e32 v9, 0xbfb8aa3b, v130
	v_exp_f32_e32 v9, v9
	v_exp_f32_e32 v121, v120
	global_store_dword v[122:123], v8, off
	v_mul_f32_e32 v8, 0x45800000, v126
	v_pk_mul_f32 v[122:123], v[132:133], v[132:133]
	v_pk_mul_f32 v[124:125], v[134:135], v[134:135]
	v_cndmask_b32_e32 v8, v126, v8, vcc
	v_add_f32_e32 v9, 1.0, v9
	v_mov_b32_e32 v126, v124
	v_mov_b32_e32 v127, v122
	v_mov_b32_e32 v122, v125
	v_rcp_f32_e32 v120, v9
	v_add_f32_e32 v9, 1.0, v121
	v_pk_add_f32 v[122:123], v[126:127], v[122:123]
	v_rcp_f32_e32 v121, v9
	ds_bpermute_b32 v125, v112, v123
	ds_bpermute_b32 v124, v112, v122
	v_pk_mul_f32 v[8:9], v[128:129], v[8:9] op_sel_hi:[1,0]
	v_pk_mul_f32 v[120:121], v[120:121], v[130:131]
	v_pk_mul_f32 v[8:9], v[222:223], v[8:9]
	s_nop 0
	v_pk_mul_f32 v[8:9], v[120:121], v[8:9]
	s_waitcnt lgkmcnt(0)
	v_pk_add_f32 v[120:121], v[122:123], v[124:125]
	ds_bpermute_b32 v123, v113, v121
	ds_bpermute_b32 v122, v113, v120
	v_cvt_pk_bf16_f32 v124, v8, v9
	s_waitcnt lgkmcnt(0)
	v_pk_add_f32 v[8:9], v[120:121], v[122:123]
	ds_bpermute_b32 v121, v114, v9
	ds_bpermute_b32 v120, v114, v8
	v_lshl_add_u64 v[122:123], v[4:5], 0, s[0:1]
	global_store_dword v[122:123], v124, off
	v_lshlrev_b32_e32 v122, 16, v119
	v_and_b32_e32 v123, 0xffff0000, v119
	s_waitcnt lgkmcnt(0)
	v_pk_add_f32 v[8:9], v[8:9], v[120:121]
	ds_bpermute_b32 v121, v115, v9
	ds_bpermute_b32 v120, v115, v8
	v_mul_f32_e32 v119, 0xbfb8aa3b, v122
	v_exp_f32_e32 v119, v119
	v_mul_f32_e32 v124, 0xbfb8aa3b, v123
	v_exp_f32_e32 v125, v124
	s_waitcnt lgkmcnt(0)
	v_pk_add_f32 v[8:9], v[8:9], v[120:121]
	ds_bpermute_b32 v121, v116, v9
	ds_bpermute_b32 v120, v116, v8
	v_add_f32_e32 v119, 1.0, v119
	v_rcp_f32_e32 v124, v119
	v_add_f32_e32 v119, 1.0, v125
	v_rcp_f32_e32 v125, v119
	s_waitcnt lgkmcnt(0)
	v_pk_add_f32 v[8:9], v[8:9], v[120:121]
	ds_bpermute_b32 v121, v117, v9
	ds_bpermute_b32 v120, v117, v8
	s_add_u32 s0, s4, s35
	v_pk_mul_f32 v[122:123], v[124:125], v[122:123]
	s_addc_u32 s1, s17, 0
	s_lshl_b64 s[0:1], s[0:1], 13
	s_waitcnt lgkmcnt(0)
	v_pk_add_f32 v[8:9], v[8:9], v[120:121]
	v_lshlrev_b32_e32 v120, 16, v118
	v_pk_fma_f32 v[6:7], v[8:9], s[8:9], v[6:7] op_sel_hi:[1,0,0]
	v_and_b32_e32 v121, 0xffff0000, v118
	v_mul_f32_e32 v8, 0x4b800000, v7
	v_cmp_gt_f32_e32 vcc, s41, v7
	v_cndmask_b32_e32 v7, v7, v8, vcc
	v_rsq_f32_e32 v7, v7
	v_lshl_add_u64 v[8:9], v[4:5], 0, s[0:1]
	s_add_u32 s0, s4, s37
	s_addc_u32 s1, s17, 0
	v_mul_f32_e32 v118, 0x45800000, v7
	v_cndmask_b32_e32 v118, v7, v118, vcc
	v_pk_mul_f32 v[118:119], v[132:133], v[118:119] op_sel_hi:[1,0]
	v_cmp_gt_f32_e32 vcc, s41, v6
	v_pk_mul_f32 v[118:119], v[222:223], v[118:119]
	s_lshl_b64 s[0:1], s[0:1], 13
	v_pk_mul_f32 v[118:119], v[122:123], v[118:119]
	s_xor_b32 s42, s42, 1
	v_cvt_pk_bf16_f32 v7, v118, v119
	global_store_dword v[8:9], v7, off
	v_mul_f32_e32 v7, 0x4b800000, v6
	v_cndmask_b32_e32 v6, v6, v7, vcc
	v_rsq_f32_e32 v8, v6
	v_mul_f32_e32 v6, 0xbfb8aa3b, v120
	v_mul_f32_e32 v7, 0xbfb8aa3b, v121
	v_exp_f32_e32 v6, v6
	v_exp_f32_e32 v7, v7
	v_mul_f32_e32 v9, 0x45800000, v8
	v_cndmask_b32_e32 v8, v8, v9, vcc
	v_add_f32_e32 v6, 1.0, v6
	v_add_f32_e32 v7, 1.0, v7
	v_rcp_f32_e32 v6, v6
	v_rcp_f32_e32 v7, v7
	v_pk_mul_f32 v[8:9], v[134:135], v[8:9] op_sel_hi:[1,0]
	s_andn2_b64 vcc, exec, s[14:15]
	v_pk_mul_f32 v[2:3], v[222:223], v[8:9]
	v_pk_mul_f32 v[6:7], v[6:7], v[120:121]
	s_mov_b32 s17, s13
	v_pk_mul_f32 v[2:3], v[6:7], v[2:3]
	v_cvt_pk_bf16_f32 v6, v2, v3
	v_lshl_add_u64 v[2:3], v[4:5], 0, s[0:1]
	global_store_dword v[2:3], v6, off
	s_cbranch_vccz .LBB0_1503
.LBB0_1499:
	s_waitcnt vmcnt(45)
	v_mfma_f32_32x32x16_bf16 v[2:17], v[18:21], v[26:29], 0
	s_lshl_b32 s0, s42, 15
	s_add_i32 s45, s0, 0
	s_add_i32 s0, s45, s22
	s_add_i32 s0, s23, s0
	s_add_i32 s12, s44, s96
	s_waitcnt vmcnt(31)
	v_lshlrev_b32_e32 v126, 16, v94
	s_waitcnt vmcnt(30)
	v_lshlrev_b32_e32 v127, 16, v95
	v_mfma_f32_32x32x16_bf16 v[2:17], v[22:25], v[30:33], v[2:17]
	v_lshlrev_b32_e32 v142, 2, v175
	s_cmpk_gt_i32 s12, 0x7ff
	s_waitcnt vmcnt(29)
	v_lshlrev_b32_e32 v128, 16, v96
	s_waitcnt vmcnt(28)
	v_lshlrev_b32_e32 v129, 16, v97
	s_waitcnt vmcnt(27)
	v_lshlrev_b32_e32 v130, 16, v98
	s_waitcnt vmcnt(26)
	v_lshlrev_b32_e32 v131, 16, v99
	s_waitcnt vmcnt(25)
	v_lshlrev_b32_e32 v132, 16, v100
	v_mfma_f32_32x32x16_bf16 v[2:17], v[34:37], v[42:45], v[2:17]
	s_waitcnt vmcnt(24)
	v_lshlrev_b32_e32 v133, 16, v101
	s_waitcnt vmcnt(23)
	v_lshlrev_b32_e32 v134, 16, v102
	s_waitcnt vmcnt(22)
	v_lshlrev_b32_e32 v135, 16, v103
	s_waitcnt vmcnt(21)
	v_lshlrev_b32_e32 v136, 16, v104
	s_waitcnt vmcnt(20)
	v_lshlrev_b32_e32 v137, 16, v105
	s_waitcnt vmcnt(19)
	v_lshlrev_b32_e32 v138, 16, v106
	s_waitcnt vmcnt(18)
	v_lshlrev_b32_e32 v139, 16, v107
	v_mfma_f32_32x32x16_bf16 v[2:17], v[38:41], v[46:49], v[2:17]
	s_waitcnt vmcnt(17)
	v_lshlrev_b32_e32 v140, 16, v108
	s_waitcnt vmcnt(16)
	v_lshlrev_b32_e32 v141, 16, v109
	v_add3_u32 v142, s0, v111, v142
	s_cselect_b64 s[14:15], -1, 0
	s_cmpk_lt_i32 s12, 0x800
	s_mov_b64 s[0:1], -1
	v_mfma_f32_32x32x16_bf16 v[2:17], v[50:53], v[58:61], v[2:17]
	v_mfma_f32_32x32x16_bf16 v[2:17], v[54:57], v[62:65], v[2:17]
	v_mfma_f32_32x32x16_bf16 v[2:17], v[66:69], v[74:77], v[2:17]
	v_mfma_f32_32x32x16_bf16 v[2:17], v[70:73], v[78:81], v[2:17]
	s_nop 11
	v_add_f32_e32 v2, v2, v126
	v_add_f32_e32 v3, v3, v127
	v_add_f32_e32 v4, v4, v128
	v_add_f32_e32 v5, v5, v129
	v_add_f32_e32 v6, v6, v130
	v_add_f32_e32 v7, v7, v131
	v_add_f32_e32 v8, v8, v132
	v_add_f32_e32 v9, v9, v133
	v_add_f32_e32 v10, v10, v134
	v_add_f32_e32 v11, v11, v135
	v_add_f32_e32 v12, v12, v136
	v_add_f32_e32 v13, v13, v137
	v_add_f32_e32 v14, v14, v138
	v_add_f32_e32 v15, v15, v139
	v_add_f32_e32 v16, v16, v140
	v_add_f32_e32 v17, v17, v141
	ds_write2st64_b32 v142, v2, v3 offset1:2
	ds_write2st64_b32 v142, v4, v5 offset0:4 offset1:6
	ds_write2st64_b32 v142, v6, v7 offset0:16 offset1:18
	ds_write2st64_b32 v142, v8, v9 offset0:20 offset1:22
	ds_write2st64_b32 v142, v10, v11 offset0:32 offset1:34
	ds_write2st64_b32 v142, v12, v13 offset0:36 offset1:38
	ds_write2st64_b32 v142, v14, v15 offset0:48 offset1:50
	ds_write2st64_b32 v142, v16, v17 offset0:52 offset1:54
	s_cbranch_scc1 .LBB0_1501
	s_add_i32 s13, s17, s39
	s_add_i32 s43, s16, s40
	s_mov_b64 s[0:1], 0
.LBB0_1501:
	s_andn2_b64 vcc, exec, s[0:1]
	s_waitcnt vmcnt(7)
	v_mov_b32_e32 v125, v224
	v_mov_b32_e32 v124, v225
	v_mov_b32_e32 v123, v226
	v_mov_b32_e32 v122, v227
	v_mov_b32_e32 v121, v228
	v_mov_b32_e32 v120, v229
	v_mov_b32_e32 v119, v230
	v_mov_b32_e32 v118, v231
	s_cbranch_vccnz .LBB0_1498
	s_ashr_i32 s0, s12, 9
	s_add_i32 s43, s40, s16
	s_ashr_i32 s13, s12, 31
	s_ashr_i32 s1, s0, 31
	s_and_b32 s4, s43, 0x7c0
	s_lshl_b64 s[46:47], s[12:13], 14
	s_lshl_b64 s[48:49], s[12:13], 15
	v_lshl_add_u64 v[2:3], v[82:83], 0, s[46:47]
	v_lshl_add_u64 v[4:5], v[84:85], 0, s[48:49]
	s_lshl_b64 s[0:1], s[0:1], 11
	s_add_i32 s4, s4, s18
	global_load_dwordx4 v[18:21], v[2:3], off
	global_load_dwordx4 v[22:25], v[2:3], off offset:32
	global_load_dwordx4 v[26:29], v[4:5], off
	global_load_dwordx4 v[30:33], v[4:5], off offset:1024
	global_load_dwordx4 v[34:37], v[2:3], off offset:64
	global_load_dwordx4 v[38:41], v[2:3], off offset:96
	global_load_dwordx4 v[42:45], v[4:5], off offset:2048
	global_load_dwordx4 v[46:49], v[4:5], off offset:3072
	v_add_co_u32_e32 v4, vcc, s11, v4
	s_add_u32 s0, s0, s4
	s_nop 0
	v_addc_co_u32_e32 v5, vcc, 0, v5, vcc
	global_load_dwordx4 v[50:53], v[2:3], off offset:128
	global_load_dwordx4 v[54:57], v[2:3], off offset:160
	global_load_dwordx4 v[58:61], v[4:5], off
	global_load_dwordx4 v[62:65], v[4:5], off offset:1024
	global_load_dwordx4 v[66:69], v[2:3], off offset:192
	global_load_dwordx4 v[70:73], v[2:3], off offset:224
	global_load_dwordx4 v[74:77], v[4:5], off offset:2048
	global_load_dwordx4 v[78:81], v[4:5], off offset:3072
	v_lshl_add_u64 v[2:3], v[92:93], 0, s[46:47]
	s_addc_u32 s1, s1, 0
	s_add_i32 s13, s39, s17
	global_load_ushort v94, v[2:3], off
	global_load_ushort v95, v[2:3], off offset:256
	global_load_ushort v96, v[2:3], off offset:512
	global_load_ushort v97, v[2:3], off offset:768
	global_load_ushort v98, v[2:3], off offset:2048
	global_load_ushort v99, v[2:3], off offset:2304
	global_load_ushort v100, v[2:3], off offset:2560
	global_load_ushort v101, v[2:3], off offset:2816
	v_add_co_u32_e32 v2, vcc, s11, v2
	s_and_b32 s4, s13, 0x780
	s_nop 0
	v_addc_co_u32_e32 v3, vcc, 0, v3, vcc
	s_lshl_b32 s4, s4, 1
	global_load_ushort v102, v[2:3], off
	global_load_ushort v103, v[2:3], off offset:256
	global_load_ushort v104, v[2:3], off offset:512
	global_load_ushort v105, v[2:3], off offset:768
	global_load_ushort v106, v[2:3], off offset:2048
	global_load_ushort v107, v[2:3], off offset:2304
	global_load_ushort v108, v[2:3], off offset:2560
	global_load_ushort v109, v[2:3], off offset:2816
	v_lshl_add_u64 v[2:3], v[86:87], 0, s[4:5]
	s_mul_i32 s4, s1, 0x7000
	v_mad_u64_u32 v[2:3], s[0:1], s0, v1, v[2:3]
	v_add_u32_e32 v3, s4, v3
	v_add_co_u32_e32 v4, vcc, s19, v2
	s_nop 1
	v_addc_co_u32_e32 v5, vcc, 0, v3, vcc
	v_add_co_u32_e32 v6, vcc, s20, v2
	s_nop 1
	v_addc_co_u32_e32 v7, vcc, 0, v3, vcc
	v_add_co_u32_e32 v8, vcc, s21, v2
	s_nop 1
	v_addc_co_u32_e32 v9, vcc, 0, v3, vcc
	v_add_co_u32_e32 v14, vcc, 0x1c000, v2
	s_nop 1
	v_addc_co_u32_e32 v15, vcc, 0, v3, vcc
	v_add_co_u32_e32 v16, vcc, 0x23000, v2
	s_nop 1
	v_addc_co_u32_e32 v17, vcc, 0, v3, vcc
	v_add_co_u32_e32 v126, vcc, 0x2a000, v2
	s_nop 1
	v_addc_co_u32_e32 v127, vcc, 0, v3, vcc
	v_add_co_u32_e32 v128, vcc, 0x31000, v2
	s_nop 1
	v_addc_co_u32_e32 v129, vcc, 0, v3, vcc
	global_load_dword v224, v[2:3], off
	global_load_dword v225, v[4:5], off
	global_load_dword v226, v[6:7], off
	global_load_dword v227, v[8:9], off
	s_nop 0
	global_load_dword v228, v[14:15], off
	s_nop 0
	global_load_dword v229, v[16:17], off
	s_nop 0
	global_load_dword v230, v[126:127], off
	global_load_dword v231, v[128:129], off
	s_branch .LBB0_1498
